# pass A prologue: kk normalisation as sqrt, max, rcp, mul (hardware f32 sqrt/rcp) instead of IEEE sqrt + IEEE divide per token: 160 fewer vector instructions per unit
# speedup vs baseline: 1.0131x; 1.0131x over previous
.LBB0_698:
	v_cndmask_b32_e64 v29, v34, 0, s[24:25]
	v_readlane_b32 s80, v233, 39
	v_add_f32_e32 v34, v35, v29
	v_readlane_b32 s81, v233, 40
	v_readlane_b32 s0, v233, 41
	v_readlane_b32 s1, v233, 42
	v_cndmask_b32_e64 v29, v29, v34, s[80:81]
	v_add_f32_e32 v32, v32, v29
	v_cndmask_b32_e64 v29, v29, v32, s[0:1]
	v_readlane_b32 s0, v233, 43
	v_add_f32_e32 v32, v33, v29
	v_readlane_b32 s1, v233, 44
	s_nop 1
	v_cndmask_b32_e64 v29, v29, v32, s[0:1]
	v_readlane_b32 s0, v233, 45
	v_add_f32_e32 v30, v30, v29
	v_readlane_b32 s1, v233, 46
	s_nop 0
	s_nop 0
	v_cndmask_b32_e64 v29, v29, v30, s[0:1]
	v_readlane_b32 s0, v233, 47
	v_add_f32_e32 v31, v31, v29
	v_readlane_b32 s1, v233, 48
	s_nop 1
	v_cndmask_b32_e64 v29, v29, v31, s[0:1]
	v_add_f32_e32 v18, v18, v29
	s_nop 1
	s_nop 0
	v_readlane_b32 s0, v233, 49
	v_readlane_b32 s1, v233, 50
	s_nop 1
	v_cndmask_b32_e64 v18, v29, v18, s[0:1]
	v_readlane_b32 s0, v233, 51
	v_add_f32_e32 v19, v19, v18
	v_readlane_b32 s1, v233, 52
	s_nop 1
	v_cndmask_b32_e64 v18, v18, v19, s[0:1]
	v_sqrt_f32_e32 v19, s46
	s_nop 0
	v_max_f32_e32 v19, 0x2b8cbccc, v19
	v_rcp_f32_e32 v19, v19
	s_nop 0
	v_mul_f32_e32 v19, v112, v19
	v_add_f32_e32 v109, v109, v18
	v_mul_f32_e32 v17, v19, v17
	v_sqrt_f32_e32 v29, s19
	s_nop 0
	v_max_f32_e32 v29, 0x2b8cbccc, v29
	v_rcp_f32_e32 v29, v29
	s_nop 0
	v_mul_f32_e32 v29, v111, v29
	v_mul_f32_e32 v15, v29, v15
	s_nop 0
	v_sqrt_f32_e32 v30, s18
	s_nop 0
	v_max_f32_e32 v30, 0x2b8cbccc, v30
	v_rcp_f32_e32 v30, v30
	s_nop 0
	v_mul_f32_e32 v114, v110, v30
	v_mul_f32_e32 v16, v114, v16
	s_nop 0
	v_sqrt_f32_e32 v30, s17
	s_nop 0
	v_max_f32_e32 v30, 0x2b8cbccc, v30
	v_rcp_f32_e32 v30, v30
	s_nop 0
	v_mul_f32_e32 v104, v104, v30
	v_mul_f32_e32 v14, v104, v14
	s_nop 0
	v_sqrt_f32_e32 v30, s9
	s_nop 0
	v_max_f32_e32 v30, 0x2b8cbccc, v30
	v_rcp_f32_e32 v30, v30
	s_nop 0
	v_mul_f32_e32 v100, v100, v30
	v_mul_f32_e32 v13, v100, v13
	s_nop 0
	v_sqrt_f32_e32 v30, s8
	s_nop 0
	v_max_f32_e32 v30, 0x2b8cbccc, v30
	v_rcp_f32_e32 v30, v30
	s_nop 0
	v_mul_f32_e32 v115, v99, v30
	v_lshlrev_b32_e32 v110, 16, v61
	v_mov_b32_e32 v111, s6
	v_mul_f32_e32 v11, v115, v11
	s_nop 0
	v_and_b32_e32 v31, 0xffff0000, v88
	v_sqrt_f32_e32 v30, s7
	s_nop 0
	v_max_f32_e32 v30, 0x2b8cbccc, v30
	v_rcp_f32_e32 v30, v30
	s_nop 0
	v_mul_f32_e32 v116, v98, v30
	v_lshlrev_b32_e32 v30, 16, v88
	v_lshlrev_b32_e32 v33, 16, v54
	v_lshlrev_b32_e32 v35, 16, v52
	v_lshlrev_b32_e32 v34, 16, v45
	v_mov_b32_e32 v32, v31
	v_pk_add_f32 v[30:31], v[30:31], v[34:35] neg_lo:[0,1] neg_hi:[0,1]
	v_pk_add_f32 v[98:99], v[34:35], v[32:33] neg_lo:[0,1] neg_hi:[0,1]
	v_pk_fma_f32 v[30:31], v[24:25], v[30:31], v[34:35] op_sel_hi:[0,1,1]
	v_pk_fma_f32 v[34:35], v[98:99], v[24:25], v[32:33] op_sel_hi:[1,0,1]
	v_mul_f32_e32 v32, s6, v79
	v_cmp_lt_f32_e32 vcc, s6, v78
	v_lshlrev_b32_e32 v99, 16, v66
	v_lshlrev_b32_e32 v98, 16, v56
	v_cndmask_b32_e32 v112, v111, v32, vcc
	v_sqrt_f32_e32 v113, v112
	v_lshlrev_b32_e32 v111, 16, v71
	v_pk_mov_b32 v[32:33], v[32:33], v[110:111] op_sel:[1,0]
	v_mul_f32_e32 v12, v116, v12
	v_add_u32_e32 v117, -1, v113
	v_fma_f32 v118, -v117, v113, v112
	v_cmp_ge_f32_e64 s[0:1], 0, v118
	v_add_u32_e32 v118, 1, v113
	v_pk_add_f32 v[32:33], v[32:33], v[98:99] neg_lo:[0,1] neg_hi:[0,1]
	v_cndmask_b32_e64 v117, v113, v117, s[0:1]
	v_fma_f32 v113, -v118, v113, v112
	v_cmp_lt_f32_e64 s[0:1], 0, v113
	v_pk_fma_f32 v[32:33], v[32:33], v[24:25], v[98:99] op_sel_hi:[1,0,1]
	s_nop 0
	v_cndmask_b32_e64 v113, v117, v118, s[0:1]
	v_mul_f32_e32 v117, 0x37800000, v113
	v_cndmask_b32_e32 v113, v113, v117, vcc
	v_cmp_class_f32_e32 vcc, v112, v77
	s_nop 1
	v_cndmask_b32_e32 v112, v113, v112, vcc
	v_max_f32_e32 v117, 0x2b8cbccc, v112
	v_div_scale_f32 v118, s[0:1], v117, v117, v97
	v_pk_add_f32 v[112:113], v[98:99], v[110:111] neg_lo:[0,1] neg_hi:[0,1]
	s_nop 0
	v_pk_fma_f32 v[98:99], v[112:113], v[24:25], v[110:111] op_sel_hi:[1,0,1]
	v_sqrt_f32_e32 v110, s6
	s_nop 0
	v_max_f32_e32 v110, 0x2b8cbccc, v110
	v_rcp_f32_e32 v110, v110
	s_nop 0
	v_mul_f32_e32 v97, v97, v110
	v_mul_f32_e32 v110, 0x3fb8aa3b, v18
	v_exp_f32_e32 v111, v110
	v_mul_f32_e32 v110, 0x3fb8aa3b, v109
	v_exp_f32_e32 v112, v110
	v_mul_f32_e32 v109, 0xbfb8aa3b, v109
	v_exp_f32_e32 v110, v109
	v_mul_f32_e32 v10, v97, v10
	v_mul_f32_e64 v97, v111, -v97
	v_mul_f32_e32 v96, v96, v112
	v_cvt_pk_bf16_f32 v109, v97, s0
	v_cvt_pk_bf16_f32 v96, v96, s0
	v_mul_f32_e32 v97, v10, v110
	v_mul_f32_e32 v111, v0, v110
	v_cvt_pk_bf16_f32 v113, v30, v31
	v_lshl_add_u32 v30, v28, 1, s74
	v_add_f32_e32 v31, v108, v18
	v_cvt_pk_bf16_f32 v97, v97, s0
	v_cvt_pk_bf16_f32 v111, v111, s0
	ds_write_b16 v30, v109
	ds_write_b16 v30, v96 offset:9216
	ds_write_b16 v30, v97 offset:18432
	ds_write_b16 v30, v111 offset:27648
	v_mul_f32_e32 v96, 0x3fb8aa3b, v31
	v_mul_f32_e32 v31, 0xbfb8aa3b, v31
	v_exp_f32_e32 v97, v96
	v_exp_f32_e32 v96, v31
	v_mul_f32_e64 v31, v112, -v116
	v_cvt_pk_bf16_f32 v112, v34, v35
	v_add_f32_e32 v34, v107, v18
	v_mul_f32_e32 v111, v4, v96
	v_mul_f32_e32 v35, 0x3fb8aa3b, v34
	v_cvt_pk_bf16_f32 v31, v31, s0
	v_mul_f32_e32 v94, v94, v97
	v_mul_f32_e32 v108, v12, v96
	v_cvt_pk_bf16_f32 v111, v111, s0
	v_exp_f32_e32 v35, v35
	v_mul_f32_e32 v34, 0xbfb8aa3b, v34
	v_cvt_pk_bf16_f32 v94, v94, s0
	v_cvt_pk_bf16_f32 v108, v108, s0
	ds_write_b16 v30, v31 offset:144
	ds_write_b16 v30, v94 offset:9360
	ds_write_b16 v30, v108 offset:18576
	ds_write_b16 v30, v111 offset:27792
	v_exp_f32_e32 v111, v34
	v_mul_f32_e64 v34, v97, -v115
	v_cvt_pk_bf16_f32 v94, v34, s0
	v_mul_f32_e32 v34, v92, v35
	v_cvt_pk_bf16_f32 v34, v34, s0
	v_mul_f32_e32 v92, v11, v111
	v_mul_f32_e32 v97, v1, v111
	v_cvt_pk_bf16_f32 v92, v92, s0
	v_cvt_pk_bf16_f32 v97, v97, s0
	ds_write_b16 v30, v94 offset:288
	ds_write_b16 v30, v34 offset:9504
	ds_write_b16 v30, v92 offset:18720
	ds_write_b16 v30, v97 offset:27936
	v_add_f32_e32 v34, v106, v18
	v_mul_f32_e32 v92, 0x3fb8aa3b, v34
	v_exp_f32_e32 v92, v92
	v_mul_f32_e32 v34, 0xbfb8aa3b, v34
	v_exp_f32_e32 v97, v34
	v_mul_f32_e64 v34, v35, -v100
	v_cvt_pk_bf16_f32 v100, v34, s0
	v_mul_f32_e32 v34, v90, v92
	v_cvt_pk_bf16_f32 v34, v34, s0
	v_mul_f32_e32 v35, v13, v97
	v_mul_f32_e32 v90, v5, v97
	v_cvt_pk_bf16_f32 v35, v35, s0
	v_cvt_pk_bf16_f32 v90, v90, s0
	ds_write_b16 v30, v100 offset:432
	ds_write_b16 v30, v34 offset:9648
	ds_write_b16 v30, v35 offset:18864
	ds_write_b16 v30, v90 offset:28080
	v_add_f32_e32 v34, v105, v18
	v_mul_f32_e32 v35, 0x3fb8aa3b, v34
	v_exp_f32_e32 v35, v35
	v_mul_f32_e32 v34, 0xbfb8aa3b, v34
	v_exp_f32_e32 v34, v34
	v_mul_f32_e64 v90, v92, -v104
	v_cvt_pk_bf16_f32 v105, v32, v33
	v_add_f32_e32 v32, v103, v18
	v_cvt_pk_bf16_f32 v92, v90, s0
	v_mul_f32_e32 v90, v95, v35
	v_mul_f32_e32 v33, 0x3fb8aa3b, v32
	v_cvt_pk_bf16_f32 v90, v90, s0
	v_mul_f32_e32 v95, v14, v34
	v_mul_f32_e32 v104, v6, v34
	v_exp_f32_e32 v33, v33
	v_mul_f32_e32 v32, 0xbfb8aa3b, v32
	v_cvt_pk_bf16_f32 v95, v95, s0
	v_cvt_pk_bf16_f32 v104, v104, s0
	ds_write_b16 v30, v92 offset:576
	ds_write_b16 v30, v90 offset:9792
	ds_write_b16 v30, v95 offset:19008
	ds_write_b16 v30, v104 offset:28224
	v_exp_f32_e32 v90, v32
	v_mul_f32_e64 v32, v35, -v114
	v_mul_f32_e32 v35, v93, v33
	v_cvt_pk_bf16_f32 v32, v32, s0
	v_cvt_pk_bf16_f32 v35, v35, s0
	v_mul_f32_e32 v93, v16, v90
	v_mul_f32_e32 v95, v8, v90
	v_cvt_pk_bf16_f32 v93, v93, s0
	v_cvt_pk_bf16_f32 v95, v95, s0
	ds_write_b16 v30, v32 offset:720
	ds_write_b16 v30, v35 offset:9936
	ds_write_b16 v30, v93 offset:19152
	ds_write_b16 v30, v95 offset:28368
	v_add_f32_e32 v35, v102, v18
	v_mul_f32_e32 v93, 0x3fb8aa3b, v35
	v_exp_f32_e32 v93, v93
	v_mul_f32_e32 v35, 0xbfb8aa3b, v35
	v_exp_f32_e32 v35, v35
	v_mul_f32_e64 v29, v33, -v29
	v_mul_f32_e32 v33, v91, v93
	v_cvt_pk_bf16_f32 v29, v29, s0
	v_cvt_pk_bf16_f32 v33, v33, s0
	v_mul_f32_e32 v91, v15, v35
	v_mul_f32_e32 v95, v7, v35
	v_add_f32_e32 v18, v101, v18
	v_cvt_pk_bf16_f32 v91, v91, s0
	v_cvt_pk_bf16_f32 v95, v95, s0
	ds_write_b16 v30, v29 offset:864
	ds_write_b16 v30, v33 offset:10080
	ds_write_b16 v30, v91 offset:19296
	ds_write_b16 v30, v95 offset:28512
	v_mul_f32_e32 v33, 0x3fb8aa3b, v18
	v_exp_f32_e32 v33, v33
	v_mul_f32_e32 v18, 0xbfb8aa3b, v18
	v_exp_f32_e32 v91, v18
	v_mul_f32_e64 v18, v93, -v19
	v_mul_f32_e32 v19, v89, v33
	v_cvt_pk_bf16_f32 v18, v18, s0
	v_cvt_pk_bf16_f32 v19, v19, s0
	v_mul_f32_e32 v33, v17, v91
	v_mul_f32_e32 v89, v9, v91
	v_cvt_pk_bf16_f32 v33, v33, s0
	v_cvt_pk_bf16_f32 v89, v89, s0
	ds_write_b16 v30, v18 offset:1008
	ds_write_b16 v30, v19 offset:10224
	ds_write_b16 v30, v33 offset:19440
	ds_write_b16 v30, v89 offset:28656
	v_lshlrev_b32_e32 v19, 16, v31
	v_or_b32_sdwa v30, v19, v109 dst_sel:DWORD dst_unused:UNUSED_PAD src0_sel:DWORD src1_sel:WORD_0
	v_lshlrev_b32_e32 v19, 16, v100
	v_lshlrev_b32_e32 v18, 16, v18
	v_or_b32_sdwa v31, v19, v94 dst_sel:DWORD dst_unused:UNUSED_PAD src0_sel:DWORD src1_sel:WORD_0
	v_lshlrev_b32_e32 v19, 16, v32
	v_or_b32_sdwa v33, v18, v29 dst_sel:DWORD dst_unused:UNUSED_PAD src0_sel:DWORD src1_sel:WORD_0
	v_mul_lo_u32 v18, v28, s76
	v_or_b32_sdwa v32, v19, v92 dst_sel:DWORD dst_unused:UNUSED_PAD src0_sel:DWORD src1_sel:WORD_0
	v_add_u32_e32 v29, s53, v18
	v_pk_mul_f32 v[18:19], v[2:3], v[110:111] op_sel_hi:[0,1]
	ds_write_b128 v29, v[30:33] offset:36864
	v_pk_mul_f32 v[30:31], v[2:3], v[96:97] op_sel_hi:[0,1]
	v_pk_mul_f32 v[10:11], v[10:11], v[18:19]
	v_pk_mul_f32 v[0:1], v[0:1], v[18:19]
	v_cvt_pk_bf16_f32 v32, v10, v11
	v_pk_mul_f32 v[10:11], v[12:13], v[30:31]
	v_cvt_pk_bf16_f32 v98, v98, v99
	v_cvt_pk_bf16_f32 v10, v10, v11
	v_and_b32_e32 v11, 0xffff0000, v10
	v_lshlrev_b32_e32 v10, 16, v10
	v_or_b32_sdwa v11, v11, v32 dst_sel:DWORD dst_unused:UNUSED_PAD src0_sel:DWORD src1_sel:WORD_1
	v_or_b32_sdwa v10, v10, v32 dst_sel:DWORD dst_unused:UNUSED_PAD src0_sel:DWORD src1_sel:WORD_0
	v_pk_mul_f32 v[32:33], v[2:3], v[34:35] op_sel_hi:[0,1]
	v_pk_mul_f32 v[34:35], v[2:3], v[90:91] op_sel_hi:[0,1]
	v_pk_mul_f32 v[12:13], v[14:15], v[32:33]
	s_mov_b64 s[0:1], -1
	v_cvt_pk_bf16_f32 v2, v12, v13
	v_pk_mul_f32 v[12:13], v[16:17], v[34:35]
	s_and_b64 vcc, exec, s[80:81]
	v_cvt_pk_bf16_f32 v12, v12, v13
	v_and_b32_e32 v13, 0xffff0000, v12
	v_lshlrev_b32_e32 v12, 16, v12
	v_or_b32_sdwa v13, v13, v2 dst_sel:DWORD dst_unused:UNUSED_PAD src0_sel:DWORD src1_sel:WORD_1
	v_or_b32_sdwa v12, v12, v2 dst_sel:DWORD dst_unused:UNUSED_PAD src0_sel:DWORD src1_sel:WORD_0
	v_cvt_pk_bf16_f32 v2, v0, v1
	v_pk_mul_f32 v[0:1], v[4:5], v[30:31]
	ds_write_b128 v29, v[10:13] offset:46080
	v_cvt_pk_bf16_f32 v0, v0, v1
	v_and_b32_e32 v1, 0xffff0000, v0
	v_lshlrev_b32_e32 v0, 16, v0
	v_or_b32_sdwa v5, v1, v2 dst_sel:DWORD dst_unused:UNUSED_PAD src0_sel:DWORD src1_sel:WORD_1
	v_or_b32_sdwa v4, v0, v2 dst_sel:DWORD dst_unused:UNUSED_PAD src0_sel:DWORD src1_sel:WORD_0
	v_pk_mul_f32 v[0:1], v[6:7], v[32:33]
	v_mov_b32_e32 v12, s55
	v_cvt_pk_bf16_f32 v2, v0, v1
	v_pk_mul_f32 v[0:1], v[8:9], v[34:35]
	s_nop 0
	v_cvt_pk_bf16_f32 v0, v0, v1
	v_and_b32_e32 v1, 0xffff0000, v0
	v_lshlrev_b32_e32 v0, 16, v0
	v_or_b32_sdwa v7, v1, v2 dst_sel:DWORD dst_unused:UNUSED_PAD src0_sel:DWORD src1_sel:WORD_1
	v_or_b32_sdwa v6, v0, v2 dst_sel:DWORD dst_unused:UNUSED_PAD src0_sel:DWORD src1_sel:WORD_0
	v_and_b32_e32 v0, 0xffff0000, v112
	v_lshlrev_b32_e32 v1, 16, v112
	ds_write_b128 v29, v[4:7] offset:55296
	v_or_b32_sdwa v5, v0, v113 dst_sel:DWORD dst_unused:UNUSED_PAD src0_sel:DWORD src1_sel:WORD_1
	v_or_b32_sdwa v4, v1, v113 dst_sel:DWORD dst_unused:UNUSED_PAD src0_sel:DWORD src1_sel:WORD_0
	v_and_b32_e32 v0, 0xffff0000, v98
	v_lshlrev_b32_e32 v1, 16, v98
	v_or_b32_sdwa v7, v0, v105 dst_sel:DWORD dst_unused:UNUSED_PAD src0_sel:DWORD src1_sel:WORD_1
	v_or_b32_sdwa v6, v1, v105 dst_sel:DWORD dst_unused:UNUSED_PAD src0_sel:DWORD src1_sel:WORD_0
	ds_write_b128 v29, v[4:7] offset:64512
	s_waitcnt lgkmcnt(0)
	s_barrier
	s_nop 0
	v_and_b32_e32 v0, 15, v28
	v_or_b32_e32 v92, s57, v0
	v_and_b32_e32 v1, -16, v28
	v_mul_u32_u24_e32 v34, 0x90, v92
	v_mad_u32_u24 v12, v0, s76, v12
	v_add3_u32 v4, s54, v34, v1
	v_add_u32_e32 v30, v12, v1
	ds_read_b128 v[8:11], v4
	ds_read_b128 v[4:7], v4 offset:64
	ds_read_b128 v[16:19], v30
	ds_read_b128 v[12:15], v30 offset:64
	v_ashrrev_i32_e32 v2, 4, v28
	v_lshlrev_b32_e32 v29, 2, v2
	v_lshlrev_b32_e32 v2, 3, v2
	v_add_u32_e32 v33, s56, v2
	v_or_b32_e32 v89, v29, v69
	v_or_b32_e32 v32, 2, v29
	v_or_b32_e32 v31, 3, v29
	v_add_u32_e32 v34, v33, v34
	s_cbranch_vccz .LBB0_700
	s_waitcnt lgkmcnt(1)
	v_mfma_f32_16x16x32_bf16 v[94:97], v[16:19], v[8:11], 0
	v_cmp_lt_i32_e32 vcc, v29, v92
	s_mov_b64 s[0:1], 0
	s_nop 0
	v_cndmask_b32_e64 v35, 0, 1, vcc
	v_cmp_le_i32_e32 vcc, v29, v92
	s_waitcnt lgkmcnt(0)
	v_mfma_f32_16x16x32_bf16 v[94:97], v[12:15], v[4:7], v[94:97]
	v_cndmask_b32_e64 v90, 0, 1, vcc
	v_cndmask_b32_e64 v35, v90, v35, s[20:21]
	v_and_b32_e32 v35, 1, v35
	v_mov_b32_e32 v90, s16
	v_cmp_eq_u32_e32 vcc, 1, v35
	s_nop 2
	v_cndmask_b32_e32 v35, v90, v94, vcc
	v_cmp_gt_i32_e32 vcc, v92, v89
	s_nop 1
	v_cndmask_b32_e32 v90, 0, v95, vcc
	v_cmp_lt_i32_e32 vcc, v32, v92
	v_cvt_pk_bf16_f32 v90, v35, v90
	s_nop 0
	v_cndmask_b32_e64 v91, 0, 1, vcc
	v_cmp_le_i32_e32 vcc, v32, v92
	s_nop 1
	v_cndmask_b32_e64 v93, 0, 1, vcc
	v_cndmask_b32_e64 v91, v93, v91, s[20:21]
	v_and_b32_e32 v91, 1, v91
	v_cmp_eq_u32_e32 vcc, 1, v91
	s_nop 1
	v_cndmask_b32_e32 v91, 0, v96, vcc
	v_cmp_lt_i32_e32 vcc, v31, v92
	s_nop 1
	v_cndmask_b32_e64 v93, 0, 1, vcc
	v_cmp_le_i32_e32 vcc, v31, v92
	s_nop 1
	v_cndmask_b32_e64 v94, 0, 1, vcc
	v_cndmask_b32_e64 v93, v94, v93, s[20:21]
	v_and_b32_e32 v93, 1, v93
	v_cmp_eq_u32_e32 vcc, 1, v93
	s_nop 1
	v_cndmask_b32_e32 v93, 0, v97, vcc
	v_cvt_pk_bf16_f32 v91, v91, v93
	ds_write_b64 v34, v[90:91]
